# fused-LN stat slots published with plain stores in group mode (same-XCD panel owners), sc1 kept otherwise
# speedup vs baseline: 1.0161x; 1.0032x over previous
;     __device__ __forceinline__ void fused(f32x4 (&acc)[2][2][4][2], const GUnit& u, int wr, int wc, int fr, int fq, LAS unsigned char* lds, int wid, int lane) const {
;     ...
;         const int prow = wid * 32 + (lane & 31);
;         if (lane < 32) {
;             const f32x2 a = P[prow * 4 + 0], b = P[prow * 4 + 1], c = P[prow * 4 + 2], d = P[prow * 4 + 3];
;             const float mt = (a.x + b.x + c.x + d.x) * 0.25f;
;             const float da = a.x - mt, db = b.x - mt, dc = c.x - mt, dd = d.x - mt;
;             const float m2 = (a.y + b.y) + (c.y + d.y) + 64.0f * ((da * da + db * db) + (dc * dc + dd * dd));
;             unsigned long long* slot = (unsigned long long*)xbuf + ((size_t)(u.pm * 256 + prow) * 4 + u.pn);
;             __hip_atomic_store(slot, ((unsigned long long)__float_as_uint(m2) << 32) | __float_as_uint(mt), __ATOMIC_RELAXED, __HIP_MEMORY_SCOPE_AGENT);
;         }
;         asm volatile("s_waitcnt vmcnt(0)" ::: "memory");
;         if (lane == 0) __hip_atomic_fetch_add(cnt + 64 * u.pm, 1u, __ATOMIC_RELAXED, __HIP_MEMORY_SCOPE_AGENT);
.LBB0_449:
	s_or_b64 exec, exec, s[2:3]
	v_readlane_b32 s2, v251, 8
	s_waitcnt lgkmcnt(0)
	s_barrier
	v_cmp_gt_i32_e64 s[4:5], 32, v32
	v_and_or_b32 v134, v32, 31, s2
	v_add_u32_e32 v132, s14, v134
	v_ashrrev_i32_e32 v133, 31, v132
	s_and_saveexec_b64 s[2:3], s[4:5]
	s_cbranch_execz .LBB0_451
	s_waitcnt lgkmcnt(0)
	v_mov_b32_e32 v146, 0x24970
	ds_read_b32 v146, v146
	v_lshl_add_u32 v135, v134, 5, 0
	ds_read_b128 v[136:139], v135
	ds_read_b128 v[140:143], v135 offset:16
	v_readlane_b32 s6, v252, 14
	v_readlane_b32 s7, v252, 15
	s_ashr_i32 s35, s34, 31
	s_waitcnt lgkmcnt(1)
	v_add_f32_e32 v135, v136, v138
	s_waitcnt lgkmcnt(0)
	v_add_f32_e32 v135, v135, v140
	v_add_f32_e32 v135, v135, v142
	v_fmamk_f32 v136, v135, 0xbe800000, v136
	v_fmac_f32_e32 v138, 0xbe800000, v135
	v_fmamk_f32 v140, v135, 0xbe800000, v140
	v_fmac_f32_e32 v142, 0xbe800000, v135
	v_mul_f32_e32 v147, v136, v136
	v_mul_f32_e32 v149, v138, v138
	v_mul_f32_e32 v151, v140, v140
	v_mul_f32_e32 v153, v142, v142
	v_mov_b32_e32 v146, v137
	v_mov_b32_e32 v148, v139
	v_mov_b32_e32 v150, v141
	v_mov_b32_e32 v152, v143
	v_pk_add_f32 v[136:137], v[146:147], v[148:149]
	v_pk_add_f32 v[138:139], v[150:151], v[152:153]
	v_mul_f32_e32 v144, 0x3e800000, v135
	v_pk_add_f32 v[136:137], v[136:137], v[138:139]
	v_lshlrev_b64 v[138:139], 5, v[132:133]
	v_fmac_f32_e32 v136, 0x42800000, v137
	v_lshl_add_u64 v[138:139], s[6:7], 0, v[138:139]
	v_lshl_add_u64 v[138:139], s[34:35], 3, v[138:139]
	v_mov_b32_e32 v145, v136
	v_readfirstlane_b32 s98, v146
	s_nop 3
	s_cmp_eq_u32 s98, 0
	s_cbranch_scc1 .Lslot_sc1
	global_store_dwordx2 v[138:139], v[144:145], off
	s_branch .Lslot_done
.Lslot_sc1:
	global_store_dwordx2 v[138:139], v[144:145], off sc1
.Lslot_done:
.LBB0_451:
	s_or_b64 exec, exec, s[2:3]
	v_readlane_b32 s2, v255, 7
	v_readlane_b32 s3, v255, 8
	s_and_b64 s[2:3], s[2:3], exec
	s_cselect_b32 s2, 0, 0x4000
	s_lshl_b32 s3, s72, 15
	s_or_b32 s2, s3, s2
	v_readlane_b32 s3, v251, 20
	s_waitcnt vmcnt(0)
	s_add_u32 s10, s3, s2
	v_readlane_b32 s2, v251, 21
	s_addc_u32 s11, s2, 0
	v_cmp_eq_u32_e64 s[6:7], 0, v32
	s_and_saveexec_b64 s[2:3], s[6:7]
	s_cbranch_execz .LBB0_454
	s_mov_b64 s[8:9], exec
	v_mbcnt_lo_u32_b32 v32, s8, 0
	v_mbcnt_hi_u32_b32 v32, s9, v32
	v_cmp_eq_u32_e32 vcc, 0, v32
	s_and_b64 s[12:13], exec, vcc
	s_mov_b64 exec, s[12:13]
	s_cbranch_execz .LBB0_454
	s_lshl_b32 s12, s37, 6
	s_ashr_i32 s13, s12, 31
	s_lshl_b64 s[12:13], s[12:13], 2
	s_add_u32 s12, s10, s12
	s_addc_u32 s13, s11, s13
	s_bcnt1_i32_b64 s8, s[8:9]
	v_mov_b32_e32 v32, s8
	global_atomic_add v33, v32, s[12:13]
